# conv/GLA summary phase too: decay projection on f32 matrix cores + two-pass LDS running sum (replaces the VALU compute_b); its w_gk2/bias operands loaded in fragment order up front
# speedup vs baseline: 1.0051x; 1.0022x over previous
.LBB0_385:
	s_or_b64 exec, exec, s[6:7]
	v_lshlrev_b32_e32 v76, 1, v18
	v_mov_b32_e32 v77, 0
	v_lshl_add_u64 v[80:81], s[4:5], 0, v[76:77]
	v_lshl_add_u64 v[114:115], s[58:59], 0, v[76:77]
	s_mov_b64 s[4:5], 0x6c00000
	v_lshl_add_u64 v[82:83], v[114:115], 0, s[4:5]
	v_lshlrev_b64 v[20:21], 10, v[78:79]
	v_or_b32_e32 v116, 1, v78
	v_lshl_add_u64 v[22:23], v[80:81], 0, v[20:21]
	v_lshl_add_u64 v[20:21], v[82:83], 0, v[20:21]
	v_ashrrev_i32_e32 v117, 31, v116
	global_load_dwordx4 v[98:101], v[22:23], off
	global_load_dwordx4 v[102:105], v[20:21], off
	v_lshlrev_b64 v[20:21], 10, v[116:117]
	v_or_b32_e32 v86, 2, v78
	v_lshl_add_u64 v[22:23], v[80:81], 0, v[20:21]
	v_lshl_add_u64 v[20:21], v[82:83], 0, v[20:21]
	v_ashrrev_i32_e32 v87, 31, v86
	global_load_dwordx4 v[106:109], v[22:23], off
	global_load_dwordx4 v[110:113], v[20:21], off
	v_lshlrev_b64 v[20:21], 10, v[86:87]
	v_or_b32_e32 v84, 3, v78
	v_lshl_add_u64 v[22:23], v[80:81], 0, v[20:21]
	v_lshl_add_u64 v[20:21], v[82:83], 0, v[20:21]
	v_ashrrev_i32_e32 v85, 31, v84
	global_load_dwordx4 v[50:53], v[22:23], off
	global_load_dwordx4 v[54:57], v[20:21], off
	v_lshlrev_b64 v[20:21], 10, v[84:85]
	v_lshl_add_u64 v[22:23], v[80:81], 0, v[20:21]
	v_lshl_add_u64 v[20:21], v[82:83], 0, v[20:21]
	global_load_dwordx4 v[42:45], v[22:23], off
	global_load_dwordx4 v[46:49], v[20:21], off
	v_lshlrev_b32_e32 v26, 2, v18
	v_mov_b32_e32 v27, v77
	v_lshl_add_u64 v[28:29], s[38:39], 0, v[26:27]
	s_movk_i32 s1, 0x1000
	global_load_dwordx4 v[18:21], v26, s[38:39] offset:2064
	global_load_dwordx4 v[30:33], v26, s[38:39] offset:2048
	global_load_dwordx4 v[22:25], v26, s[38:39] offset:16
	global_load_dwordx4 v[34:37], v26, s[38:39]
	v_add_co_u32_e32 v26, vcc, s1, v28
	s_mov_b64 s[4:5], 0x1000
	s_nop 0
	v_addc_co_u32_e32 v27, vcc, 0, v29, vcc
	global_load_dwordx4 v[38:41], v[26:27], off
	v_lshl_add_u64 v[26:27], v[28:29], 0, s[4:5]
	global_load_dwordx4 v[26:29], v[26:27], off offset:16
	v_or_b32_e32 v184, 5, v78
	v_ashrrev_i32_e32 v185, 31, v184
	v_lshlrev_b64 v[184:185], 10, v[184:185]
	v_or_b32_e32 v186, 4, v78
	v_ashrrev_i32_e32 v187, 31, v186
	v_lshlrev_b64 v[186:187], 10, v[186:187]
	v_or_b32_e32 v188, 7, v78
	v_ashrrev_i32_e32 v189, 31, v188
	v_lshlrev_b64 v[188:189], 10, v[188:189]
	v_or_b32_e32 v190, 6, v78
	v_ashrrev_i32_e32 v191, 31, v190
	v_lshlrev_b64 v[190:191], 10, v[190:191]
	v_lshl_add_u64 v[192:193], v[82:83], 0, v[184:185]
	global_load_dwordx4 v[152:155], v[192:193], off
	v_lshl_add_u64 v[192:193], v[82:83], 0, v[186:187]
	global_load_dwordx4 v[156:159], v[192:193], off
	v_lshl_add_u64 v[192:193], v[80:81], 0, v[186:187]
	global_load_dwordx4 v[160:163], v[192:193], off
	v_lshl_add_u64 v[192:193], v[80:81], 0, v[184:185]
	global_load_dwordx4 v[164:167], v[192:193], off
	v_lshl_add_u64 v[192:193], v[82:83], 0, v[188:189]
	global_load_dwordx4 v[168:171], v[192:193], off
	v_lshl_add_u64 v[192:193], v[80:81], 0, v[188:189]
	global_load_dwordx4 v[172:175], v[192:193], off
	v_lshl_add_u64 v[192:193], v[82:83], 0, v[190:191]
	global_load_dwordx4 v[176:179], v[192:193], off
	v_lshl_add_u64 v[192:193], v[80:81], 0, v[190:191]
	global_load_dwordx4 v[180:183], v[192:193], off
	v_lshrrev_b32_e32 v188, 6, v0
	v_or_b32_e32 v188, s0, v188
	v_lshlrev_b32_e32 v189, 4, v1
	s_movk_i32 s98, 0xc00
	v_mul_lo_u32 v188, v188, s98
	v_add_u32_e32 v188, v188, v189
	global_load_dwordx4 v[212:215], v188, s[2:3] offset:1024
	v_add_u32_e32 v190, 0x6000, v188
	global_load_dwordx4 v[216:219], v190, s[2:3] offset:1024
	v_add_u32_e32 v190, 0xc000, v188
	global_load_dwordx4 v[220:223], v190, s[2:3] offset:1024
	v_add_u32_e32 v190, 0x12000, v188
	global_load_dwordx4 v[224:227], v190, s[2:3] offset:1024
	v_add_u32_e32 v190, 0x18000, v188
	global_load_dwordx4 v[228:231], v190, s[2:3] offset:1024
	v_add_u32_e32 v190, 0x1e000, v188
	global_load_dwordx4 v[232:235], v190, s[2:3] offset:1024
	v_add_u32_e32 v190, 0x24000, v188
	global_load_dwordx4 v[236:239], v190, s[2:3] offset:1024
	v_add_u32_e32 v190, 0x2a000, v188
	global_load_dwordx4 v[240:243], v190, s[2:3] offset:1024
	v_readlane_b32 s98, v254, 20
	v_lshrrev_b32_e32 v184, 4, v1
	v_and_b32_e32 v185, 15, v1
	v_lshlrev_b32_e32 v184, 12, v184
	s_lshl_b32 s98, s98, 7
	v_lshl_add_u32 v185, v185, 2, s98
	v_add_u32_e32 v184, v184, v185
	global_load_dword v244, v184, s[40:41]
	global_load_dword v245, v184, s[40:41] offset:1024
	global_load_dword v246, v184, s[40:41] offset:2048
	global_load_dword v247, v184, s[40:41] offset:3072
	global_load_dword v248, v184, s[40:41] offset:64
	global_load_dword v249, v184, s[40:41] offset:1088
	global_load_dword v250, v184, s[40:41] offset:2112
	global_load_dword v251, v184, s[40:41] offset:3136
	global_load_dword v252, v185, s[42:43]
	global_load_dword v253, v185, s[42:43] offset:64
	s_mov_b64 s[4:5], 0x4c00000
	s_waitcnt vmcnt(40)
	v_lshlrev_b32_e32 v122, 16, v58
	v_and_b32_e32 v123, 0xffff0000, v58
	v_lshlrev_b32_e32 v126, 16, v59
	v_and_b32_e32 v127, 0xffff0000, v59
	v_lshlrev_b32_e32 v132, 16, v60
	v_and_b32_e32 v133, 0xffff0000, v60
	v_lshlrev_b32_e32 v136, 16, v61
	v_and_b32_e32 v137, 0xffff0000, v61
	v_lshlrev_b64 v[60:61], 11, v[78:79]
	v_lshl_add_u64 v[58:59], v[114:115], 0, s[4:5]
	v_lshlrev_b32_e32 v120, 16, v62
	v_and_b32_e32 v121, 0xffff0000, v62
	v_lshlrev_b32_e32 v62, 16, v63
	v_and_b32_e32 v63, 0xffff0000, v63
	v_lshlrev_b32_e32 v130, 16, v64
	v_and_b32_e32 v131, 0xffff0000, v64
	v_lshlrev_b32_e32 v64, 16, v65
	v_and_b32_e32 v65, 0xffff0000, v65
	v_lshl_add_u64 v[114:115], v[58:59], 0, v[60:61]
	s_waitcnt vmcnt(39)
	v_lshlrev_b32_e32 v124, 16, v98
	v_and_b32_e32 v125, 0xffff0000, v98
	v_lshlrev_b32_e32 v128, 16, v99
	v_and_b32_e32 v129, 0xffff0000, v99
	v_lshlrev_b32_e32 v134, 16, v100
	v_and_b32_e32 v135, 0xffff0000, v100
	v_lshlrev_b32_e32 v138, 16, v101
	v_and_b32_e32 v139, 0xffff0000, v101
	s_waitcnt vmcnt(38)
	v_lshlrev_b32_e32 v118, 16, v102
	v_and_b32_e32 v119, 0xffff0000, v102
	v_lshlrev_b32_e32 v102, 16, v103
	v_and_b32_e32 v103, 0xffff0000, v103
	v_lshlrev_b32_e32 v98, 16, v104
	v_and_b32_e32 v99, 0xffff0000, v104
	v_lshlrev_b32_e32 v104, 16, v105
	v_and_b32_e32 v105, 0xffff0000, v105
	s_waitcnt vmcnt(36)
	v_lshlrev_b32_e32 v100, 16, v110
	v_and_b32_e32 v101, 0xffff0000, v110
	v_lshlrev_b32_e32 v110, 16, v111
	v_and_b32_e32 v111, 0xffff0000, v111
	v_lshlrev_b32_e32 v140, 16, v106
	v_and_b32_e32 v141, 0xffff0000, v106
	s_waitcnt vmcnt(35)
	v_lshlrev_b32_e32 v106, 16, v50
	s_waitcnt vmcnt(31)
	v_pk_mul_f32 v[144:145], v[18:19], v[132:133]
	s_waitcnt vmcnt(30)
	v_pk_mul_f32 v[60:61], v[30:31], v[122:123]
	v_pk_mul_f32 v[142:143], v[32:33], v[126:127]
	v_pk_mul_f32 v[146:147], v[20:21], v[136:137]
	s_waitcnt vmcnt(28)
	v_pk_fma_f32 v[60:61], v[34:35], v[120:121], v[60:61]
	v_pk_fma_f32 v[62:63], v[36:37], v[62:63], v[142:143]
	v_pk_fma_f32 v[120:121], v[22:23], v[130:131], v[144:145]
	v_pk_fma_f32 v[64:65], v[24:25], v[64:65], v[146:147]
	s_waitcnt vmcnt(27)
	v_pk_fma_f32 v[60:61], v[38:39], v[124:125], v[60:61]
	v_pk_fma_f32 v[62:63], v[40:41], v[128:129], v[62:63]
	s_waitcnt vmcnt(26)
	v_pk_fma_f32 v[120:121], v[26:27], v[134:135], v[120:121]
	v_pk_fma_f32 v[64:65], v[28:29], v[138:139], v[64:65]
	v_pk_mul_f32 v[60:61], v[60:61], v[118:119]
	v_pk_mul_f32 v[62:63], v[62:63], v[102:103]
	v_pk_mul_f32 v[98:99], v[120:121], v[98:99]
	v_pk_mul_f32 v[64:65], v[64:65], v[104:105]
	v_pk_mul_f32 v[150:151], v[32:33], v[128:129]
	v_cvt_pk_bf16_f32 v60, v60, v61
	v_cvt_pk_bf16_f32 v61, v62, v63
	v_cvt_pk_bf16_f32 v62, v98, v99
	v_cvt_pk_bf16_f32 v63, v64, v65
	global_store_dwordx4 v[114:115], v[60:63], off
	v_pk_mul_f32 v[64:65], v[18:19], v[134:135]
	v_pk_mul_f32 v[148:149], v[30:31], v[124:125]
	v_pk_fma_f32 v[60:61], v[36:37], v[126:127], v[150:151]
	v_lshlrev_b32_e32 v62, 16, v107
	v_and_b32_e32 v63, 0xffff0000, v107
	v_pk_fma_f32 v[60:61], v[40:41], v[62:63], v[60:61]
	v_pk_fma_f32 v[64:65], v[22:23], v[132:133], v[64:65]
	v_pk_mul_f32 v[60:61], v[60:61], v[110:111]
	v_lshlrev_b32_e32 v102, 16, v108
	v_and_b32_e32 v103, 0xffff0000, v108
	v_pk_fma_f32 v[122:123], v[34:35], v[122:123], v[148:149]
	v_cvt_pk_bf16_f32 v99, v60, v61
	v_lshlrev_b32_e32 v60, 16, v112
	v_and_b32_e32 v61, 0xffff0000, v112
	v_pk_fma_f32 v[64:65], v[26:27], v[102:103], v[64:65]
	v_pk_fma_f32 v[122:123], v[38:39], v[140:141], v[122:123]
	v_pk_mul_f32 v[60:61], v[64:65], v[60:61]
	v_pk_mul_f32 v[64:65], v[20:21], v[138:139]
	v_pk_mul_f32 v[100:101], v[122:123], v[100:101]
	v_pk_fma_f32 v[64:65], v[24:25], v[136:137], v[64:65]
	v_lshlrev_b32_e32 v104, 16, v109
	v_and_b32_e32 v105, 0xffff0000, v109
	v_cvt_pk_bf16_f32 v98, v100, v101
	v_cvt_pk_bf16_f32 v100, v60, v61
	v_lshlrev_b32_e32 v60, 16, v113
	v_and_b32_e32 v61, 0xffff0000, v113
	v_pk_fma_f32 v[64:65], v[28:29], v[104:105], v[64:65]
	v_and_b32_e32 v107, 0xffff0000, v50
	v_pk_mul_f32 v[60:61], v[64:65], v[60:61]
	v_pk_mul_f32 v[64:65], v[30:31], v[140:141]
	v_cvt_pk_bf16_f32 v101, v60, v61
	v_lshlrev_b64 v[60:61], 11, v[116:117]
	v_lshl_add_u64 v[60:61], v[58:59], 0, v[60:61]
	v_pk_fma_f32 v[64:65], v[34:35], v[124:125], v[64:65]
	global_store_dwordx4 v[60:61], v[98:101], off
	v_lshlrev_b32_e32 v60, 16, v54
	v_and_b32_e32 v61, 0xffff0000, v54
	v_pk_fma_f32 v[64:65], v[38:39], v[106:107], v[64:65]
	v_lshlrev_b32_e32 v54, 16, v55
	v_pk_mul_f32 v[60:61], v[64:65], v[60:61]
	v_lshlrev_b32_e32 v64, 16, v51
	v_cvt_pk_bf16_f32 v50, v60, v61
	v_pk_mul_f32 v[60:61], v[32:33], v[62:63]
	v_and_b32_e32 v65, 0xffff0000, v51
	v_pk_fma_f32 v[60:61], v[36:37], v[128:129], v[60:61]
	v_and_b32_e32 v55, 0xffff0000, v55
	v_pk_fma_f32 v[60:61], v[40:41], v[64:65], v[60:61]
	v_lshlrev_b32_e32 v108, 16, v52
	v_pk_mul_f32 v[54:55], v[60:61], v[54:55]
	v_pk_mul_f32 v[60:61], v[18:19], v[102:103]
	v_and_b32_e32 v109, 0xffff0000, v52
	v_pk_fma_f32 v[60:61], v[22:23], v[134:135], v[60:61]
	v_cvt_pk_bf16_f32 v51, v54, v55
	v_lshlrev_b32_e32 v54, 16, v56
	v_and_b32_e32 v55, 0xffff0000, v56
	v_pk_fma_f32 v[60:61], v[26:27], v[108:109], v[60:61]
	v_lshlrev_b32_e32 v110, 16, v53
	v_pk_mul_f32 v[54:55], v[60:61], v[54:55]
	v_and_b32_e32 v111, 0xffff0000, v53
	v_cvt_pk_bf16_f32 v52, v54, v55
	v_lshlrev_b32_e32 v54, 16, v57
	v_and_b32_e32 v55, 0xffff0000, v57
	v_pk_mul_f32 v[56:57], v[20:21], v[104:105]
	v_lshlrev_b32_e32 v112, 16, v42
	v_pk_fma_f32 v[56:57], v[24:25], v[138:139], v[56:57]
	v_and_b32_e32 v113, 0xffff0000, v42
	v_pk_fma_f32 v[56:57], v[28:29], v[110:111], v[56:57]
	v_lshlrev_b32_e32 v114, 16, v43
	v_pk_mul_f32 v[54:55], v[56:57], v[54:55]
	v_and_b32_e32 v115, 0xffff0000, v43
	v_cvt_pk_bf16_f32 v53, v54, v55
	v_lshlrev_b64 v[54:55], 11, v[86:87]
	v_lshl_add_u64 v[54:55], v[58:59], 0, v[54:55]
	global_store_dwordx4 v[54:55], v[50:53], off
	v_or_b32_e32 v116, 4, v78
	v_ashrrev_i32_e32 v117, 31, v116
	v_pk_mul_f32 v[52:53], v[30:31], v[106:107]
	v_lshlrev_b32_e32 v50, 16, v46
	v_pk_fma_f32 v[52:53], v[34:35], v[140:141], v[52:53]
	v_and_b32_e32 v51, 0xffff0000, v46
	v_pk_fma_f32 v[52:53], v[38:39], v[112:113], v[52:53]
	v_lshlrev_b32_e32 v46, 16, v47
	v_pk_mul_f32 v[50:51], v[52:53], v[50:51]
	v_and_b32_e32 v47, 0xffff0000, v47
	v_cvt_pk_bf16_f32 v42, v50, v51
	v_pk_mul_f32 v[50:51], v[32:33], v[64:65]
	v_or_b32_e32 v118, 5, v78
	v_pk_fma_f32 v[50:51], v[36:37], v[62:63], v[50:51]
	v_ashrrev_i32_e32 v119, 31, v118
	v_pk_fma_f32 v[50:51], v[40:41], v[114:115], v[50:51]
	v_lshlrev_b64 v[54:55], 10, v[118:119]
	v_pk_mul_f32 v[46:47], v[50:51], v[46:47]
	v_pk_mul_f32 v[50:51], v[18:19], v[108:109]
	v_cvt_pk_bf16_f32 v43, v46, v47
	v_pk_fma_f32 v[50:51], v[22:23], v[102:103], v[50:51]
	v_lshlrev_b32_e32 v102, 16, v44
	v_and_b32_e32 v103, 0xffff0000, v44
	v_lshlrev_b32_e32 v46, 16, v48
	v_and_b32_e32 v47, 0xffff0000, v48
	v_pk_fma_f32 v[50:51], v[26:27], v[102:103], v[50:51]
	v_or_b32_e32 v120, 7, v78
	v_pk_mul_f32 v[46:47], v[50:51], v[46:47]
	v_lshl_add_u64 v[50:51], v[82:83], 0, v[54:55]
	v_cvt_pk_bf16_f32 v44, v46, v47
	v_lshlrev_b32_e32 v46, 16, v49
	v_and_b32_e32 v47, 0xffff0000, v49
	v_pk_mul_f32 v[48:49], v[20:21], v[110:111]
	v_lshl_add_u64 v[54:55], v[80:81], 0, v[54:55]
	v_pk_fma_f32 v[48:49], v[24:25], v[104:105], v[48:49]
	v_lshlrev_b32_e32 v104, 16, v45
	v_and_b32_e32 v105, 0xffff0000, v45
	v_pk_fma_f32 v[48:49], v[28:29], v[104:105], v[48:49]
	v_or_b32_e32 v122, 6, v78
	v_pk_mul_f32 v[46:47], v[48:49], v[46:47]
	v_ashrrev_i32_e32 v121, 31, v120
	v_cvt_pk_bf16_f32 v45, v46, v47
	v_lshlrev_b64 v[46:47], 11, v[84:85]
	v_lshl_add_u64 v[46:47], v[58:59], 0, v[46:47]
	global_store_dwordx4 v[46:47], v[42:45], off
	v_lshlrev_b64 v[46:47], 10, v[116:117]
	s_waitcnt vmcnt(22)
	v_mov_b32_e32 v50, v152
	v_mov_b32_e32 v51, v153
	v_mov_b32_e32 v52, v154
	v_mov_b32_e32 v53, v155
	v_lshl_add_u64 v[42:43], v[82:83], 0, v[46:47]
	v_lshl_add_u64 v[46:47], v[80:81], 0, v[46:47]
	v_mov_b32_e32 v42, v156
	v_mov_b32_e32 v43, v157
	v_mov_b32_e32 v44, v158
	v_mov_b32_e32 v45, v159
	v_ashrrev_i32_e32 v123, 31, v122
	v_mov_b32_e32 v46, v160
	v_mov_b32_e32 v47, v161
	v_mov_b32_e32 v48, v162
	v_mov_b32_e32 v49, v163
	v_lshlrev_b64 v[60:61], 10, v[120:121]
	v_mov_b32_e32 v54, v164
	v_mov_b32_e32 v55, v165
	v_mov_b32_e32 v56, v166
	v_mov_b32_e32 v57, v167
	v_lshlrev_b64 v[78:79], 10, v[122:123]
	v_lshl_add_u64 v[98:99], v[82:83], 0, v[60:61]
	v_lshl_add_u64 v[100:101], v[80:81], 0, v[60:61]
	v_lshl_add_u64 v[82:83], v[82:83], 0, v[78:79]
	v_mov_b32_e32 v60, v168
	v_mov_b32_e32 v61, v169
	v_mov_b32_e32 v62, v170
	v_mov_b32_e32 v63, v171
	v_mov_b32_e32 v84, v172
	v_mov_b32_e32 v85, v173
	v_mov_b32_e32 v86, v174
	v_mov_b32_e32 v87, v175
	v_lshl_add_u64 v[124:125], v[80:81], 0, v[78:79]
	v_mov_b32_e32 v78, v176
	v_mov_b32_e32 v79, v177
	v_mov_b32_e32 v80, v178
	v_mov_b32_e32 v81, v179
	v_mov_b32_e32 v98, v180
	v_mov_b32_e32 v99, v181
	v_mov_b32_e32 v100, v182
	v_mov_b32_e32 v101, v183
	v_pk_mul_f32 v[124:125], v[30:31], v[112:113]
	s_nop 0
	v_lshlrev_b32_e32 v82, 16, v42
	v_pk_fma_f32 v[106:107], v[34:35], v[106:107], v[124:125]
	s_nop 0
	v_lshlrev_b32_e32 v124, 16, v46
	v_and_b32_e32 v125, 0xffff0000, v46
	v_and_b32_e32 v83, 0xffff0000, v42
	v_pk_fma_f32 v[106:107], v[38:39], v[124:125], v[106:107]
	v_lshlrev_b32_e32 v46, 16, v47
	v_pk_mul_f32 v[82:83], v[106:107], v[82:83]
	v_pk_mul_f32 v[106:107], v[32:33], v[114:115]
	v_and_b32_e32 v47, 0xffff0000, v47
	v_pk_fma_f32 v[64:65], v[36:37], v[64:65], v[106:107]
	v_cvt_pk_bf16_f32 v42, v82, v83
	v_lshlrev_b32_e32 v82, 16, v43
	v_and_b32_e32 v83, 0xffff0000, v43
	v_pk_fma_f32 v[64:65], v[40:41], v[46:47], v[64:65]
	v_lshlrev_b32_e32 v106, 16, v48
	v_pk_mul_f32 v[64:65], v[64:65], v[82:83]
	v_pk_mul_f32 v[82:83], v[18:19], v[102:103]
	v_and_b32_e32 v107, 0xffff0000, v48
	v_pk_fma_f32 v[82:83], v[22:23], v[108:109], v[82:83]
	v_cvt_pk_bf16_f32 v43, v64, v65
	v_lshlrev_b32_e32 v64, 16, v44
	v_and_b32_e32 v65, 0xffff0000, v44
	v_pk_fma_f32 v[82:83], v[26:27], v[106:107], v[82:83]
	v_lshlrev_b32_e32 v48, 16, v49
	v_pk_mul_f32 v[64:65], v[82:83], v[64:65]
	v_pk_mul_f32 v[82:83], v[20:21], v[104:105]
	v_and_b32_e32 v49, 0xffff0000, v49
	v_pk_fma_f32 v[82:83], v[24:25], v[110:111], v[82:83]
	v_cvt_pk_bf16_f32 v44, v64, v65
	v_lshlrev_b32_e32 v64, 16, v45
	v_and_b32_e32 v65, 0xffff0000, v45
	v_pk_fma_f32 v[82:83], v[28:29], v[48:49], v[82:83]
	s_nop 0
	v_pk_mul_f32 v[64:65], v[82:83], v[64:65]
	s_nop 0
	v_lshlrev_b32_e32 v82, 16, v56
	v_cvt_pk_bf16_f32 v45, v64, v65
	v_lshlrev_b64 v[64:65], 11, v[116:117]
	v_lshl_add_u64 v[64:65], v[58:59], 0, v[64:65]
	global_store_dwordx4 v[64:65], v[42:45], off
	v_lshlrev_b32_e32 v64, 16, v54
	v_and_b32_e32 v65, 0xffff0000, v54
	v_pk_mul_f32 v[44:45], v[30:31], v[124:125]
	v_lshlrev_b32_e32 v42, 16, v50
	v_pk_fma_f32 v[44:45], v[34:35], v[112:113], v[44:45]
	v_and_b32_e32 v43, 0xffff0000, v50
	v_pk_fma_f32 v[44:45], v[38:39], v[64:65], v[44:45]
	v_lshlrev_b32_e32 v54, 16, v55
	v_pk_mul_f32 v[42:43], v[44:45], v[42:43]
	v_lshlrev_b32_e32 v44, 16, v51
	v_and_b32_e32 v45, 0xffff0000, v51
	v_pk_mul_f32 v[50:51], v[32:33], v[46:47]
	v_and_b32_e32 v55, 0xffff0000, v55
	v_pk_fma_f32 v[50:51], v[36:37], v[114:115], v[50:51]
	v_and_b32_e32 v83, 0xffff0000, v56
	v_pk_fma_f32 v[50:51], v[40:41], v[54:55], v[50:51]
	v_cvt_pk_bf16_f32 v42, v42, v43
	v_pk_mul_f32 v[44:45], v[50:51], v[44:45]
	v_pk_mul_f32 v[50:51], v[18:19], v[106:107]
	v_cvt_pk_bf16_f32 v43, v44, v45
	v_pk_fma_f32 v[50:51], v[22:23], v[102:103], v[50:51]
	v_lshlrev_b32_e32 v44, 16, v52
	v_and_b32_e32 v45, 0xffff0000, v52
	v_pk_fma_f32 v[50:51], v[26:27], v[82:83], v[50:51]
	v_lshlrev_b32_e32 v56, 16, v57
	v_pk_mul_f32 v[44:45], v[50:51], v[44:45]
	v_lshlrev_b32_e32 v50, 16, v53
	v_and_b32_e32 v51, 0xffff0000, v53
	v_pk_mul_f32 v[52:53], v[20:21], v[48:49]
	v_and_b32_e32 v57, 0xffff0000, v57
	v_pk_fma_f32 v[52:53], v[24:25], v[104:105], v[52:53]
	v_cvt_pk_bf16_f32 v44, v44, v45
	v_pk_fma_f32 v[52:53], v[28:29], v[56:57], v[52:53]
	v_pk_mul_f32 v[46:47], v[36:37], v[46:47]
	v_pk_mul_f32 v[50:51], v[52:53], v[50:51]
	v_pk_fma_f32 v[46:47], v[32:33], v[54:55], v[46:47]
	v_cvt_pk_bf16_f32 v45, v50, v51
	v_lshlrev_b64 v[50:51], 11, v[118:119]
	v_lshl_add_u64 v[50:51], v[58:59], 0, v[50:51]
	global_store_dwordx4 v[50:51], v[42:45], off
	s_nop 0
	v_lshlrev_b32_e32 v50, 16, v98
	v_and_b32_e32 v51, 0xffff0000, v98
	v_pk_mul_f32 v[44:45], v[34:35], v[124:125]
	v_lshlrev_b32_e32 v42, 16, v78
	v_pk_fma_f32 v[44:45], v[30:31], v[64:65], v[44:45]
	v_and_b32_e32 v43, 0xffff0000, v78
	v_pk_fma_f32 v[44:45], v[38:39], v[50:51], v[44:45]
	v_lshlrev_b32_e32 v52, 16, v99
	v_and_b32_e32 v53, 0xffff0000, v99
	v_pk_mul_f32 v[42:43], v[44:45], v[42:43]
	v_lshlrev_b32_e32 v44, 16, v79
	v_and_b32_e32 v45, 0xffff0000, v79
	v_pk_fma_f32 v[46:47], v[40:41], v[52:53], v[46:47]
	v_lshlrev_b32_e32 v78, 16, v100
	v_pk_mul_f32 v[44:45], v[46:47], v[44:45]
	v_pk_mul_f32 v[46:47], v[22:23], v[106:107]
	v_and_b32_e32 v79, 0xffff0000, v100
	v_pk_fma_f32 v[46:47], v[18:19], v[82:83], v[46:47]
	v_cvt_pk_bf16_f32 v42, v42, v43
	v_cvt_pk_bf16_f32 v43, v44, v45
	v_lshlrev_b32_e32 v44, 16, v80
	v_and_b32_e32 v45, 0xffff0000, v80
	v_pk_fma_f32 v[46:47], v[26:27], v[78:79], v[46:47]
	v_pk_mul_f32 v[48:49], v[24:25], v[48:49]
	v_pk_mul_f32 v[44:45], v[46:47], v[44:45]
	v_lshlrev_b32_e32 v46, 16, v81
	v_and_b32_e32 v47, 0xffff0000, v81
	v_pk_fma_f32 v[48:49], v[20:21], v[56:57], v[48:49]
	v_lshlrev_b32_e32 v80, 16, v101
	v_and_b32_e32 v81, 0xffff0000, v101
	v_pk_fma_f32 v[48:49], v[28:29], v[80:81], v[48:49]
	v_cvt_pk_bf16_f32 v44, v44, v45
	v_pk_mul_f32 v[46:47], v[48:49], v[46:47]
	v_pk_mul_f32 v[34:35], v[34:35], v[64:65]
	v_cvt_pk_bf16_f32 v45, v46, v47
	v_lshlrev_b64 v[46:47], 11, v[122:123]
	v_pk_mul_f32 v[36:37], v[36:37], v[54:55]
	v_lshl_add_u64 v[46:47], v[58:59], 0, v[46:47]
	v_pk_fma_f32 v[30:31], v[30:31], v[50:51], v[34:35]
	v_lshlrev_b32_e32 v34, 16, v84
	v_and_b32_e32 v35, 0xffff0000, v84
	v_pk_fma_f32 v[32:33], v[32:33], v[52:53], v[36:37]
	v_lshlrev_b32_e32 v36, 16, v85
	v_and_b32_e32 v37, 0xffff0000, v85
	global_store_dwordx4 v[46:47], v[42:45], off
	v_pk_fma_f32 v[30:31], v[38:39], v[34:35], v[30:31]
	v_lshlrev_b32_e32 v34, 16, v61
	v_lshlrev_b32_e32 v42, 16, v60
	v_and_b32_e32 v43, 0xffff0000, v60
	v_and_b32_e32 v35, 0xffff0000, v61
	v_pk_fma_f32 v[32:33], v[40:41], v[36:37], v[32:33]
	v_pk_mul_f32 v[22:23], v[22:23], v[82:83]
	v_pk_mul_f32 v[30:31], v[30:31], v[42:43]
	v_pk_mul_f32 v[32:33], v[32:33], v[34:35]
	v_pk_fma_f32 v[18:19], v[18:19], v[78:79], v[22:23]
	v_lshlrev_b32_e32 v22, 16, v86
	v_and_b32_e32 v23, 0xffff0000, v86
	v_cvt_pk_bf16_f32 v30, v30, v31
	v_cvt_pk_bf16_f32 v31, v32, v33
	v_lshlrev_b32_e32 v32, 16, v62
	v_and_b32_e32 v33, 0xffff0000, v62
	v_pk_fma_f32 v[18:19], v[26:27], v[22:23], v[18:19]
	v_pk_mul_f32 v[22:23], v[24:25], v[56:57]
	v_pk_mul_f32 v[18:19], v[18:19], v[32:33]
	v_pk_fma_f32 v[20:21], v[20:21], v[80:81], v[22:23]
	v_lshlrev_b32_e32 v22, 16, v87
	v_and_b32_e32 v23, 0xffff0000, v87
	v_cvt_pk_bf16_f32 v32, v18, v19
	v_lshlrev_b32_e32 v18, 16, v63
	v_and_b32_e32 v19, 0xffff0000, v63
	v_pk_fma_f32 v[20:21], v[28:29], v[22:23], v[20:21]
	s_nop 0
	v_pk_mul_f32 v[18:19], v[20:21], v[18:19]
	s_nop 0
	v_cvt_pk_bf16_f32 v33, v18, v19
	v_lshlrev_b64 v[18:19], 11, v[120:121]
	v_lshl_add_u64 v[18:19], v[58:59], 0, v[18:19]
	global_store_dwordx4 v[18:19], v[30:33], off
	v_lshrrev_b32_e32 v78, 6, v0
	v_or_b32_e32 v22, s0, v78
	s_movk_i32 s4, 0xc00
	v_mov_b64_e32 v[18:19], s[2:3]
	v_mad_i64_i32 v[20:21], s[2:3], v22, s4, v[18:19]
	v_lshrrev_b32_e32 v79, 6, v94
	v_lshl_add_u64 v[86:87], v[20:21], 0, v[76:77]
	v_or_b32_e32 v20, s0, v79
	v_mad_i64_i32 v[20:21], s[2:3], v20, s4, v[18:19]
	v_lshrrev_b32_e32 v80, 6, v95
	v_lshl_add_u64 v[98:99], v[20:21], 0, v[76:77]
	v_or_b32_e32 v20, s0, v80
	v_mad_i64_i32 v[20:21], s[2:3], v20, s4, v[18:19]
	v_lshrrev_b32_e32 v81, 6, v96
	v_lshl_add_u64 v[94:95], v[20:21], 0, v[76:77]
	v_or_b32_e32 v20, s0, v81
	v_mad_i64_i32 v[20:21], s[2:3], v20, s4, v[18:19]
	v_lshl_add_u64 v[96:97], v[20:21], 0, v[76:77]
	v_or_b32_e32 v20, 32, v22
	v_mad_i64_i32 v[20:21], s[2:3], v20, s4, v[18:19]
	v_lshl_add_u64 v[100:101], v[20:21], 0, v[76:77]
	v_or_b32_e32 v20, 0xa00, v0
	v_lshrrev_b32_e32 v82, 6, v20
	v_or_b32_e32 v20, s0, v82
	v_mad_i64_i32 v[20:21], s[2:3], v20, s4, v[18:19]
	v_lshl_add_u64 v[102:103], v[20:21], 0, v[76:77]
	v_or_b32_e32 v20, 48, v22
	v_mad_i64_i32 v[20:21], s[2:3], v20, s4, v[18:19]
	v_lshl_add_u64 v[104:105], v[20:21], 0, v[76:77]
	v_or_b32_e32 v20, 0xe00, v0
	v_lshrrev_b32_e32 v83, 6, v20
	v_add_u32_e32 v20, s0, v83
	v_mad_i64_i32 v[18:19], s[2:3], v20, s4, v[18:19]
	v_and_b32_e32 v84, 0xff, v0
	v_lshl_add_u64 v[106:107], v[18:19], 0, v[76:77]
	v_lshlrev_b32_e32 v76, 2, v84
	v_lshl_add_u64 v[18:19], s[40:41], 0, v[76:77]
	v_add_co_u32_e32 v20, vcc, s1, v18
	s_movk_i32 s0, 0x2000
	s_nop 0
	v_addc_co_u32_e32 v21, vcc, 0, v19, vcc
	v_lshlrev_b32_e32 v24, 2, v0
	v_add_co_u32_e32 v22, vcc, s0, v18
	v_or_b32_e32 v25, 0xc00, v24
	s_nop 0
	v_addc_co_u32_e32 v23, vcc, 0, v19, vcc
	v_or_b32_e32 v26, 0x1c00, v24
	s_movk_i32 s0, 0x3000
	v_add_co_u32_e32 v18, vcc, s0, v18
	v_or_b32_e32 v20, 0x2c00, v24
	s_nop 0
	v_addc_co_u32_e32 v19, vcc, 0, v19, vcc
	v_or_b32_e32 v108, 0x3c00, v24
	s_waitcnt vmcnt(8)
	v_mov_b32_e32 v46, v212
	v_mov_b32_e32 v47, v213
	v_mov_b32_e32 v48, v214
	v_mov_b32_e32 v49, v215
	v_mov_b32_e32 v42, v216
	v_mov_b32_e32 v43, v217
	v_mov_b32_e32 v44, v218
	v_mov_b32_e32 v45, v219
	v_mov_b32_e32 v38, v220
	v_mov_b32_e32 v39, v221
	v_mov_b32_e32 v40, v222
	v_mov_b32_e32 v41, v223
	v_mov_b32_e32 v30, v224
	v_mov_b32_e32 v31, v225
	v_mov_b32_e32 v32, v226
	v_mov_b32_e32 v33, v227
	v_mov_b32_e32 v34, v228
	v_mov_b32_e32 v35, v229
	v_mov_b32_e32 v36, v230
	v_mov_b32_e32 v37, v231
	v_mov_b32_e32 v22, v232
	v_mov_b32_e32 v23, v233
	v_mov_b32_e32 v24, v234
	v_mov_b32_e32 v25, v235
	v_mov_b32_e32 v26, v236
	v_mov_b32_e32 v27, v237
	v_mov_b32_e32 v28, v238
	v_mov_b32_e32 v29, v239
	v_mov_b32_e32 v18, v240
	v_mov_b32_e32 v19, v241
	v_mov_b32_e32 v20, v242
	v_mov_b32_e32 v21, v243
	v_readlane_b32 s6, v254, 18
	v_readlane_b32 s7, v254, 19
	v_pk_add_f32 v[68:69], v[68:69], v[70:71]
	v_pk_add_f32 v[70:71], v[72:73], v[74:75]
	s_ashr_i32 s7, s6, 31
	v_pk_add_f32 v[68:69], v[68:69], v[70:71]
	s_add_i32 s0, 0, 0x23000
	v_lshlrev_b32_e32 v70, 2, v67
	s_lshl_b64 s[2:3], s[6:7], 12
	v_add_u32_e32 v71, s0, v70
	s_add_u32 s2, s58, s2
	ds_write_b64 v71, v[68:69]
	s_addc_u32 s3, s59, s3
	v_mov_b32_e32 v71, v77
	v_lshl_add_u64 v[70:71], s[2:3], 0, v[70:71]
	s_mov_b32 s1, 0x200000
	v_add_co_u32_e32 v70, vcc, s1, v70
	s_mov_b32 s1, 0xbd800000
	s_nop 0
	v_addc_co_u32_e32 v71, vcc, 0, v71, vcc
	global_store_dwordx2 v[70:71], v[68:69], off
	v_and_b32_e32 v70, 32, v93
	v_lshl_add_u32 v68, v70, 6, s0
	s_waitcnt lgkmcnt(0)
	s_barrier
	v_lshrrev_b32_e32 v237, 4, v1
	v_and_b32_e32 v236, 15, v1
	v_lshlrev_b32_e32 v238, 6, v236
	v_lshl_add_u32 v238, v237, 4, v238
	v_add_u32_e32 v238, 0x23000, v238
	ds_read_b128 v[220:223], v238
	ds_read_b128 v[224:227], v238 offset:1024
	ds_read_b128 v[228:231], v238 offset:2048
	ds_read_b128 v[232:235], v238 offset:3072
	v_readlane_b32 s98, v254, 20
	v_lshlrev_b32_e32 v239, 12, v237
	v_lshl_add_u32 v239, v236, 2, v239
	s_lshl_b32 s99, s98, 7
	v_add_u32_e32 v239, s99, v239
	s_waitcnt lgkmcnt(0)
	v_mfma_f32_16x16x4_f32 v[188:191], v220, v244, 0
	v_mfma_f32_16x16x4_f32 v[192:195], v220, v248, 0
	v_mfma_f32_16x16x4_f32 v[196:199], v224, v244, 0
	v_mfma_f32_16x16x4_f32 v[200:203], v224, v248, 0
	v_mfma_f32_16x16x4_f32 v[204:207], v228, v244, 0
	v_mfma_f32_16x16x4_f32 v[208:211], v228, v248, 0
	v_mfma_f32_16x16x4_f32 v[212:215], v232, v244, 0
	v_mfma_f32_16x16x4_f32 v[216:219], v232, v248, 0
	v_mfma_f32_16x16x4_f32 v[188:191], v221, v245, v[188:191]
	v_mfma_f32_16x16x4_f32 v[192:195], v221, v249, v[192:195]
	v_mfma_f32_16x16x4_f32 v[196:199], v225, v245, v[196:199]
	v_mfma_f32_16x16x4_f32 v[200:203], v225, v249, v[200:203]
	v_mfma_f32_16x16x4_f32 v[204:207], v229, v245, v[204:207]
	v_mfma_f32_16x16x4_f32 v[208:211], v229, v249, v[208:211]
	v_mfma_f32_16x16x4_f32 v[212:215], v233, v245, v[212:215]
	v_mfma_f32_16x16x4_f32 v[216:219], v233, v249, v[216:219]
	v_mfma_f32_16x16x4_f32 v[188:191], v222, v246, v[188:191]
	v_mfma_f32_16x16x4_f32 v[192:195], v222, v250, v[192:195]
	v_mfma_f32_16x16x4_f32 v[196:199], v226, v246, v[196:199]
	v_mfma_f32_16x16x4_f32 v[200:203], v226, v250, v[200:203]
	v_mfma_f32_16x16x4_f32 v[204:207], v230, v246, v[204:207]
	v_mfma_f32_16x16x4_f32 v[208:211], v230, v250, v[208:211]
	v_mfma_f32_16x16x4_f32 v[212:215], v234, v246, v[212:215]
	v_mfma_f32_16x16x4_f32 v[216:219], v234, v250, v[216:219]
	v_mfma_f32_16x16x4_f32 v[188:191], v223, v247, v[188:191]
	v_mfma_f32_16x16x4_f32 v[192:195], v223, v251, v[192:195]
	v_mfma_f32_16x16x4_f32 v[196:199], v227, v247, v[196:199]
	v_mfma_f32_16x16x4_f32 v[200:203], v227, v251, v[200:203]
	v_mfma_f32_16x16x4_f32 v[204:207], v231, v247, v[204:207]
	v_mfma_f32_16x16x4_f32 v[208:211], v231, v251, v[208:211]
	v_mfma_f32_16x16x4_f32 v[212:215], v235, v247, v[212:215]
	v_mfma_f32_16x16x4_f32 v[216:219], v235, v251, v[216:219]
	s_nop 7
	s_nop 3
	v_add_f32_e32 v188, v188, v252
	v_add_f32_e32 v189, v189, v252
	v_add_f32_e32 v190, v190, v252
	v_add_f32_e32 v191, v191, v252
	v_max_f32_e32 v188, 0xc2a00000, v188
	v_max_f32_e32 v189, 0xc2a00000, v189
	v_max_f32_e32 v190, 0xc2a00000, v190
	v_max_f32_e32 v191, 0xc2a00000, v191
	v_mul_f32_e32 v188, 0xbfb8aa3b, v188
	v_mul_f32_e32 v189, 0xbfb8aa3b, v189
	v_mul_f32_e32 v190, 0xbfb8aa3b, v190
	v_mul_f32_e32 v191, 0xbfb8aa3b, v191
	v_exp_f32_e32 v188, v188
	v_exp_f32_e32 v189, v189
	v_exp_f32_e32 v190, v190
	v_exp_f32_e32 v191, v191
	v_add_f32_e32 v188, 1.0, v188
	v_add_f32_e32 v189, 1.0, v189
	v_add_f32_e32 v190, 1.0, v190
	v_add_f32_e32 v191, 1.0, v191
	v_log_f32_e32 v188, v188
	v_log_f32_e32 v189, v189
	v_log_f32_e32 v190, v190
	v_log_f32_e32 v191, v191
	v_mul_f32_e32 v188, 0x3f317218, v188
	v_mul_f32_e32 v189, 0x3f317218, v189
	v_mul_f32_e32 v190, 0x3f317218, v190
	v_mul_f32_e32 v191, 0x3f317218, v191
	ds_write_b32 v239, v188 offset:0
	ds_write_b32 v239, v189 offset:1024
	ds_write_b32 v239, v190 offset:2048
	ds_write_b32 v239, v191 offset:3072
	v_add_f32_e32 v192, v192, v253
	v_add_f32_e32 v193, v193, v253
	v_add_f32_e32 v194, v194, v253
	v_add_f32_e32 v195, v195, v253
	v_max_f32_e32 v192, 0xc2a00000, v192
	v_max_f32_e32 v193, 0xc2a00000, v193
	v_max_f32_e32 v194, 0xc2a00000, v194
	v_max_f32_e32 v195, 0xc2a00000, v195
	v_mul_f32_e32 v192, 0xbfb8aa3b, v192
	v_mul_f32_e32 v193, 0xbfb8aa3b, v193
	v_mul_f32_e32 v194, 0xbfb8aa3b, v194
	v_mul_f32_e32 v195, 0xbfb8aa3b, v195
	v_exp_f32_e32 v192, v192
	v_exp_f32_e32 v193, v193
	v_exp_f32_e32 v194, v194
	v_exp_f32_e32 v195, v195
	v_add_f32_e32 v192, 1.0, v192
	v_add_f32_e32 v193, 1.0, v193
	v_add_f32_e32 v194, 1.0, v194
	v_add_f32_e32 v195, 1.0, v195
	v_log_f32_e32 v192, v192
	v_log_f32_e32 v193, v193
	v_log_f32_e32 v194, v194
	v_log_f32_e32 v195, v195
	v_mul_f32_e32 v192, 0x3f317218, v192
	v_mul_f32_e32 v193, 0x3f317218, v193
	v_mul_f32_e32 v194, 0x3f317218, v194
	v_mul_f32_e32 v195, 0x3f317218, v195
	ds_write_b32 v239, v192 offset:64
	ds_write_b32 v239, v193 offset:1088
	ds_write_b32 v239, v194 offset:2112
	ds_write_b32 v239, v195 offset:3136
	v_add_f32_e32 v196, v196, v252
	v_add_f32_e32 v197, v197, v252
	v_add_f32_e32 v198, v198, v252
	v_add_f32_e32 v199, v199, v252
	v_max_f32_e32 v196, 0xc2a00000, v196
	v_max_f32_e32 v197, 0xc2a00000, v197
	v_max_f32_e32 v198, 0xc2a00000, v198
	v_max_f32_e32 v199, 0xc2a00000, v199
	v_mul_f32_e32 v196, 0xbfb8aa3b, v196
	v_mul_f32_e32 v197, 0xbfb8aa3b, v197
	v_mul_f32_e32 v198, 0xbfb8aa3b, v198
	v_mul_f32_e32 v199, 0xbfb8aa3b, v199
	v_exp_f32_e32 v196, v196
	v_exp_f32_e32 v197, v197
	v_exp_f32_e32 v198, v198
	v_exp_f32_e32 v199, v199
	v_add_f32_e32 v196, 1.0, v196
	v_add_f32_e32 v197, 1.0, v197
	v_add_f32_e32 v198, 1.0, v198
	v_add_f32_e32 v199, 1.0, v199
	v_log_f32_e32 v196, v196
	v_log_f32_e32 v197, v197
	v_log_f32_e32 v198, v198
	v_log_f32_e32 v199, v199
	v_mul_f32_e32 v196, 0x3f317218, v196
	v_mul_f32_e32 v197, 0x3f317218, v197
	v_mul_f32_e32 v198, 0x3f317218, v198
	v_mul_f32_e32 v199, 0x3f317218, v199
	ds_write_b32 v239, v196 offset:16384
	ds_write_b32 v239, v197 offset:17408
	ds_write_b32 v239, v198 offset:18432
	ds_write_b32 v239, v199 offset:19456
	v_add_f32_e32 v200, v200, v253
	v_add_f32_e32 v201, v201, v253
	v_add_f32_e32 v202, v202, v253
	v_add_f32_e32 v203, v203, v253
	v_max_f32_e32 v200, 0xc2a00000, v200
	v_max_f32_e32 v201, 0xc2a00000, v201
	v_max_f32_e32 v202, 0xc2a00000, v202
	v_max_f32_e32 v203, 0xc2a00000, v203
	v_mul_f32_e32 v200, 0xbfb8aa3b, v200
	v_mul_f32_e32 v201, 0xbfb8aa3b, v201
	v_mul_f32_e32 v202, 0xbfb8aa3b, v202
	v_mul_f32_e32 v203, 0xbfb8aa3b, v203
	v_exp_f32_e32 v200, v200
	v_exp_f32_e32 v201, v201
	v_exp_f32_e32 v202, v202
	v_exp_f32_e32 v203, v203
	v_add_f32_e32 v200, 1.0, v200
	v_add_f32_e32 v201, 1.0, v201
	v_add_f32_e32 v202, 1.0, v202
	v_add_f32_e32 v203, 1.0, v203
	v_log_f32_e32 v200, v200
	v_log_f32_e32 v201, v201
	v_log_f32_e32 v202, v202
	v_log_f32_e32 v203, v203
	v_mul_f32_e32 v200, 0x3f317218, v200
	v_mul_f32_e32 v201, 0x3f317218, v201
	v_mul_f32_e32 v202, 0x3f317218, v202
	v_mul_f32_e32 v203, 0x3f317218, v203
	ds_write_b32 v239, v200 offset:16448
	ds_write_b32 v239, v201 offset:17472
	ds_write_b32 v239, v202 offset:18496
	ds_write_b32 v239, v203 offset:19520
	v_add_f32_e32 v204, v204, v252
	v_add_f32_e32 v205, v205, v252
	v_add_f32_e32 v206, v206, v252
	v_add_f32_e32 v207, v207, v252
	v_max_f32_e32 v204, 0xc2a00000, v204
	v_max_f32_e32 v205, 0xc2a00000, v205
	v_max_f32_e32 v206, 0xc2a00000, v206
	v_max_f32_e32 v207, 0xc2a00000, v207
	v_mul_f32_e32 v204, 0xbfb8aa3b, v204
	v_mul_f32_e32 v205, 0xbfb8aa3b, v205
	v_mul_f32_e32 v206, 0xbfb8aa3b, v206
	v_mul_f32_e32 v207, 0xbfb8aa3b, v207
	v_exp_f32_e32 v204, v204
	v_exp_f32_e32 v205, v205
	v_exp_f32_e32 v206, v206
	v_exp_f32_e32 v207, v207
	v_add_f32_e32 v204, 1.0, v204
	v_add_f32_e32 v205, 1.0, v205
	v_add_f32_e32 v206, 1.0, v206
	v_add_f32_e32 v207, 1.0, v207
	v_log_f32_e32 v204, v204
	v_log_f32_e32 v205, v205
	v_log_f32_e32 v206, v206
	v_log_f32_e32 v207, v207
	v_mul_f32_e32 v204, 0x3f317218, v204
	v_mul_f32_e32 v205, 0x3f317218, v205
	v_mul_f32_e32 v206, 0x3f317218, v206
	v_mul_f32_e32 v207, 0x3f317218, v207
	ds_write_b32 v239, v204 offset:32768
	ds_write_b32 v239, v205 offset:33792
	ds_write_b32 v239, v206 offset:34816
	ds_write_b32 v239, v207 offset:35840
	v_add_f32_e32 v208, v208, v253
	v_add_f32_e32 v209, v209, v253
	v_add_f32_e32 v210, v210, v253
	v_add_f32_e32 v211, v211, v253
	v_max_f32_e32 v208, 0xc2a00000, v208
	v_max_f32_e32 v209, 0xc2a00000, v209
	v_max_f32_e32 v210, 0xc2a00000, v210
	v_max_f32_e32 v211, 0xc2a00000, v211
	v_mul_f32_e32 v208, 0xbfb8aa3b, v208
	v_mul_f32_e32 v209, 0xbfb8aa3b, v209
	v_mul_f32_e32 v210, 0xbfb8aa3b, v210
	v_mul_f32_e32 v211, 0xbfb8aa3b, v211
	v_exp_f32_e32 v208, v208
	v_exp_f32_e32 v209, v209
	v_exp_f32_e32 v210, v210
	v_exp_f32_e32 v211, v211
	v_add_f32_e32 v208, 1.0, v208
	v_add_f32_e32 v209, 1.0, v209
	v_add_f32_e32 v210, 1.0, v210
	v_add_f32_e32 v211, 1.0, v211
	v_log_f32_e32 v208, v208
	v_log_f32_e32 v209, v209
	v_log_f32_e32 v210, v210
	v_log_f32_e32 v211, v211
	v_mul_f32_e32 v208, 0x3f317218, v208
	v_mul_f32_e32 v209, 0x3f317218, v209
	v_mul_f32_e32 v210, 0x3f317218, v210
	v_mul_f32_e32 v211, 0x3f317218, v211
	ds_write_b32 v239, v208 offset:32832
	ds_write_b32 v239, v209 offset:33856
	ds_write_b32 v239, v210 offset:34880
	ds_write_b32 v239, v211 offset:35904
	v_add_f32_e32 v212, v212, v252
	v_add_f32_e32 v213, v213, v252
	v_add_f32_e32 v214, v214, v252
	v_add_f32_e32 v215, v215, v252
	v_max_f32_e32 v212, 0xc2a00000, v212
	v_max_f32_e32 v213, 0xc2a00000, v213
	v_max_f32_e32 v214, 0xc2a00000, v214
	v_max_f32_e32 v215, 0xc2a00000, v215
	v_mul_f32_e32 v212, 0xbfb8aa3b, v212
	v_mul_f32_e32 v213, 0xbfb8aa3b, v213
	v_mul_f32_e32 v214, 0xbfb8aa3b, v214
	v_mul_f32_e32 v215, 0xbfb8aa3b, v215
	v_exp_f32_e32 v212, v212
	v_exp_f32_e32 v213, v213
	v_exp_f32_e32 v214, v214
	v_exp_f32_e32 v215, v215
	v_add_f32_e32 v212, 1.0, v212
	v_add_f32_e32 v213, 1.0, v213
	v_add_f32_e32 v214, 1.0, v214
	v_add_f32_e32 v215, 1.0, v215
	v_log_f32_e32 v212, v212
	v_log_f32_e32 v213, v213
	v_log_f32_e32 v214, v214
	v_log_f32_e32 v215, v215
	v_mul_f32_e32 v212, 0x3f317218, v212
	v_mul_f32_e32 v213, 0x3f317218, v213
	v_mul_f32_e32 v214, 0x3f317218, v214
	v_mul_f32_e32 v215, 0x3f317218, v215
	ds_write_b32 v239, v212 offset:49152
	ds_write_b32 v239, v213 offset:50176
	ds_write_b32 v239, v214 offset:51200
	ds_write_b32 v239, v215 offset:52224
	v_add_f32_e32 v216, v216, v253
	v_add_f32_e32 v217, v217, v253
	v_add_f32_e32 v218, v218, v253
	v_add_f32_e32 v219, v219, v253
	v_max_f32_e32 v216, 0xc2a00000, v216
	v_max_f32_e32 v217, 0xc2a00000, v217
	v_max_f32_e32 v218, 0xc2a00000, v218
	v_max_f32_e32 v219, 0xc2a00000, v219
	v_mul_f32_e32 v216, 0xbfb8aa3b, v216
	v_mul_f32_e32 v217, 0xbfb8aa3b, v217
	v_mul_f32_e32 v218, 0xbfb8aa3b, v218
	v_mul_f32_e32 v219, 0xbfb8aa3b, v219
	v_exp_f32_e32 v216, v216
	v_exp_f32_e32 v217, v217
	v_exp_f32_e32 v218, v218
	v_exp_f32_e32 v219, v219
	v_add_f32_e32 v216, 1.0, v216
	v_add_f32_e32 v217, 1.0, v217
	v_add_f32_e32 v218, 1.0, v218
	v_add_f32_e32 v219, 1.0, v219
	v_log_f32_e32 v216, v216
	v_log_f32_e32 v217, v217
	v_log_f32_e32 v218, v218
	v_log_f32_e32 v219, v219
	v_mul_f32_e32 v216, 0x3f317218, v216
	v_mul_f32_e32 v217, 0x3f317218, v217
	v_mul_f32_e32 v218, 0x3f317218, v218
	v_mul_f32_e32 v219, 0x3f317218, v219
	ds_write_b32 v239, v216 offset:49216
	ds_write_b32 v239, v217 offset:50240
	ds_write_b32 v239, v218 offset:51264
	ds_write_b32 v239, v219 offset:52288
	s_waitcnt lgkmcnt(0)
	s_barrier
	v_and_b32_e32 v236, 0xff, v0
	s_lshr_b32 s99, s98, 2
	s_lshl_b32 s100, s99, 15
	v_lshl_add_u32 v238, v236, 2, s100
	v_mov_b32_e32 v237, 0
	ds_read_b32 v220, v238 offset:0
	ds_read_b32 v221, v238 offset:1024
	ds_read_b32 v222, v238 offset:2048
	ds_read_b32 v223, v238 offset:3072
	ds_read_b32 v224, v238 offset:4096
	ds_read_b32 v225, v238 offset:5120
	ds_read_b32 v226, v238 offset:6144
	ds_read_b32 v227, v238 offset:7168
	s_waitcnt lgkmcnt(7)
	v_fmac_f32_e32 v237, 0xbd800000, v220
	ds_write_b32 v238, v237 offset:0
	s_waitcnt lgkmcnt(7)
	v_fmac_f32_e32 v237, 0xbd800000, v221
	ds_write_b32 v238, v237 offset:1024
	s_waitcnt lgkmcnt(7)
	v_fmac_f32_e32 v237, 0xbd800000, v222
	ds_write_b32 v238, v237 offset:2048
	s_waitcnt lgkmcnt(7)
	v_fmac_f32_e32 v237, 0xbd800000, v223
	ds_write_b32 v238, v237 offset:3072
	s_waitcnt lgkmcnt(7)
	v_fmac_f32_e32 v237, 0xbd800000, v224
	ds_write_b32 v238, v237 offset:4096
	s_waitcnt lgkmcnt(7)
	v_fmac_f32_e32 v237, 0xbd800000, v225
	ds_write_b32 v238, v237 offset:5120
	s_waitcnt lgkmcnt(7)
	v_fmac_f32_e32 v237, 0xbd800000, v226
	ds_write_b32 v238, v237 offset:6144
	s_waitcnt lgkmcnt(7)
	v_fmac_f32_e32 v237, 0xbd800000, v227
	ds_write_b32 v238, v237 offset:7168
	s_waitcnt lgkmcnt(4)
	ds_read_b32 v220, v238 offset:8192
	ds_read_b32 v221, v238 offset:9216
	ds_read_b32 v222, v238 offset:10240
	ds_read_b32 v223, v238 offset:11264
	ds_read_b32 v224, v238 offset:12288
	ds_read_b32 v225, v238 offset:13312
	ds_read_b32 v226, v238 offset:14336
	ds_read_b32 v227, v238 offset:15360
	s_waitcnt lgkmcnt(7)
	v_fmac_f32_e32 v237, 0xbd800000, v220
	ds_write_b32 v238, v237 offset:8192
	s_waitcnt lgkmcnt(7)
	v_fmac_f32_e32 v237, 0xbd800000, v221
	ds_write_b32 v238, v237 offset:9216
	s_waitcnt lgkmcnt(7)
	v_fmac_f32_e32 v237, 0xbd800000, v222
	ds_write_b32 v238, v237 offset:10240
	s_waitcnt lgkmcnt(7)
	v_fmac_f32_e32 v237, 0xbd800000, v223
	ds_write_b32 v238, v237 offset:11264
	s_waitcnt lgkmcnt(7)
	v_fmac_f32_e32 v237, 0xbd800000, v224
	ds_write_b32 v238, v237 offset:12288
	s_waitcnt lgkmcnt(7)
	v_fmac_f32_e32 v237, 0xbd800000, v225
	ds_write_b32 v238, v237 offset:13312
	s_waitcnt lgkmcnt(7)
	v_fmac_f32_e32 v237, 0xbd800000, v226
	ds_write_b32 v238, v237 offset:14336
	s_waitcnt lgkmcnt(7)
	v_fmac_f32_e32 v237, 0xbd800000, v227
	ds_write_b32 v238, v237 offset:15360
	s_waitcnt lgkmcnt(4)
	ds_read_b32 v220, v238 offset:16384
	ds_read_b32 v221, v238 offset:17408
	ds_read_b32 v222, v238 offset:18432
	ds_read_b32 v223, v238 offset:19456
	ds_read_b32 v224, v238 offset:20480
	ds_read_b32 v225, v238 offset:21504
	ds_read_b32 v226, v238 offset:22528
	ds_read_b32 v227, v238 offset:23552
	s_waitcnt lgkmcnt(7)
	v_fmac_f32_e32 v237, 0xbd800000, v220
	ds_write_b32 v238, v237 offset:16384
	s_waitcnt lgkmcnt(7)
	v_fmac_f32_e32 v237, 0xbd800000, v221
	ds_write_b32 v238, v237 offset:17408
	s_waitcnt lgkmcnt(7)
	v_fmac_f32_e32 v237, 0xbd800000, v222
	ds_write_b32 v238, v237 offset:18432
	s_waitcnt lgkmcnt(7)
	v_fmac_f32_e32 v237, 0xbd800000, v223
	ds_write_b32 v238, v237 offset:19456
	s_waitcnt lgkmcnt(7)
	v_fmac_f32_e32 v237, 0xbd800000, v224
	ds_write_b32 v238, v237 offset:20480
	s_waitcnt lgkmcnt(7)
	v_fmac_f32_e32 v237, 0xbd800000, v225
	ds_write_b32 v238, v237 offset:21504
	s_waitcnt lgkmcnt(7)
	v_fmac_f32_e32 v237, 0xbd800000, v226
	ds_write_b32 v238, v237 offset:22528
	s_waitcnt lgkmcnt(7)
	v_fmac_f32_e32 v237, 0xbd800000, v227
	ds_write_b32 v238, v237 offset:23552
	s_waitcnt lgkmcnt(4)
	ds_read_b32 v220, v238 offset:24576
	ds_read_b32 v221, v238 offset:25600
	ds_read_b32 v222, v238 offset:26624
	ds_read_b32 v223, v238 offset:27648
	ds_read_b32 v224, v238 offset:28672
	ds_read_b32 v225, v238 offset:29696
	ds_read_b32 v226, v238 offset:30720
	ds_read_b32 v227, v238 offset:31744
	s_waitcnt lgkmcnt(7)
	v_fmac_f32_e32 v237, 0xbd800000, v220
	ds_write_b32 v238, v237 offset:24576
	s_waitcnt lgkmcnt(7)
	v_fmac_f32_e32 v237, 0xbd800000, v221
	ds_write_b32 v238, v237 offset:25600
	s_waitcnt lgkmcnt(7)
	v_fmac_f32_e32 v237, 0xbd800000, v222
	ds_write_b32 v238, v237 offset:26624
	s_waitcnt lgkmcnt(7)
	v_fmac_f32_e32 v237, 0xbd800000, v223
	ds_write_b32 v238, v237 offset:27648
	s_waitcnt lgkmcnt(7)
	v_fmac_f32_e32 v237, 0xbd800000, v224
	ds_write_b32 v238, v237 offset:28672
	s_waitcnt lgkmcnt(7)
	v_fmac_f32_e32 v237, 0xbd800000, v225
	ds_write_b32 v238, v237 offset:29696
	s_waitcnt lgkmcnt(7)
	v_fmac_f32_e32 v237, 0xbd800000, v226
	ds_write_b32 v238, v237 offset:30720
	s_waitcnt lgkmcnt(7)
	v_fmac_f32_e32 v237, 0xbd800000, v227
	ds_write_b32 v238, v237 offset:31744
	s_cmp_lg_u32 s99, 0
	s_cbranch_scc1 .Lcb_notot_p5
	v_lshl_add_u32 v236, v236, 2, 0
	v_add_u32_e32 v236, 0x24000, v236
	ds_write_b32 v236, v237
.Lcb_notot_p5:
	s_movk_i32 s0, 0x100
	v_cmp_gt_u32_e32 vcc, s0, v0
	v_and_b32_e32 v68, 31, v0
	v_lshl_add_u32 v84, v68, 5, 0
	v_add_u32_e32 v62, 0x24000, v84
	s_add_i32 s2, 0, 0x1a000
	v_lshl_add_u32 v86, v92, 10, v84
	s_waitcnt lgkmcnt(0)
	s_barrier
	ds_read_b128 v[54:57], v84 offset:64512
	ds_read_b128 v[50:53], v84 offset:64528
	ds_read_b128 v[58:61], v62
	ds_read_b128 v[62:65], v62 offset:16
	v_lshl_add_u32 v85, v68, 4, s2
	ds_read_b128 v[68:71], v86
	s_movk_i32 s0, 0x240
	s_waitcnt lgkmcnt(2)
	v_pk_add_f32 v[76:77], v[54:55], v[58:59]
	s_waitcnt lgkmcnt(1)
	v_pk_add_f32 v[72:73], v[52:53], v[64:65]
	v_pk_add_f32 v[74:75], v[50:51], v[62:63]
	ds_read_b128 v[62:65], v86 offset:16
	s_waitcnt lgkmcnt(1)
	v_sub_f32_e32 v58, v76, v68
	v_sub_f32_e32 v59, v77, v69
	v_mul_f32_e32 v58, 0x3fb8aa3b, v58
	v_mul_f32_e32 v59, 0x3fb8aa3b, v59
	v_exp_f32_e32 v58, v58
	v_exp_f32_e32 v59, v59
	v_pk_add_f32 v[68:69], v[56:57], v[60:61]
	v_lshlrev_b32_e32 v60, 16, v14
	v_and_b32_e32 v61, 0xffff0000, v14
	v_sub_f32_e32 v14, v68, v70
	v_mul_f32_e32 v14, 0x3fb8aa3b, v14
	v_pk_mul_f32 v[58:59], v[58:59], v[60:61]
	v_exp_f32_e32 v60, v14
	v_sub_f32_e32 v14, v69, v71
	v_mul_f32_e32 v14, 0x3fb8aa3b, v14
	v_exp_f32_e32 v61, v14
	v_cvt_pk_bf16_f32 v14, v58, v59
	v_lshlrev_b32_e32 v58, 16, v15
	v_and_b32_e32 v59, 0xffff0000, v15
	s_waitcnt lgkmcnt(0)
	v_sub_f32_e32 v15, v74, v62
	v_mul_f32_e32 v15, 0x3fb8aa3b, v15
	v_pk_mul_f32 v[58:59], v[60:61], v[58:59]
	v_exp_f32_e32 v60, v15
	v_sub_f32_e32 v15, v75, v63
	v_mul_f32_e32 v15, 0x3fb8aa3b, v15
	v_exp_f32_e32 v61, v15
	v_cvt_pk_bf16_f32 v15, v58, v59
	v_lshlrev_b32_e32 v58, 16, v16
	v_and_b32_e32 v59, 0xffff0000, v16
	v_sub_f32_e32 v16, v72, v64
	v_mul_f32_e32 v16, 0x3fb8aa3b, v16
	v_pk_mul_f32 v[58:59], v[60:61], v[58:59]
	v_exp_f32_e32 v60, v16
	v_sub_f32_e32 v16, v73, v65
	v_mul_f32_e32 v16, 0x3fb8aa3b, v16
	v_exp_f32_e32 v61, v16
	v_cvt_pk_bf16_f32 v16, v58, v59
	v_lshlrev_b32_e32 v58, 16, v17
	v_and_b32_e32 v59, 0xffff0000, v17
	v_lshl_add_u32 v64, v91, 10, v84
	v_pk_mul_f32 v[62:63], v[60:61], v[58:59]
	ds_read_b128 v[58:61], v64
	v_cvt_pk_bf16_f32 v17, v62, v63
	v_mad_u32_u24 v70, v92, s0, v85
	ds_write_b128 v70, v[14:17]
	v_lshlrev_b32_e32 v14, 16, v10
	s_waitcnt lgkmcnt(1)
	v_sub_f32_e32 v58, v76, v58
	v_sub_f32_e32 v59, v77, v59
	v_mul_f32_e32 v58, 0x3fb8aa3b, v58
	v_mul_f32_e32 v59, 0x3fb8aa3b, v59
	v_and_b32_e32 v15, 0xffff0000, v10
	v_sub_f32_e32 v10, v68, v60
	ds_read_b128 v[62:65], v64 offset:16
	v_exp_f32_e32 v58, v58
	v_exp_f32_e32 v59, v59
	v_mul_f32_e32 v10, 0x3fb8aa3b, v10
	v_exp_f32_e32 v16, v10
	v_sub_f32_e32 v10, v69, v61
	v_mul_f32_e32 v10, 0x3fb8aa3b, v10
	v_exp_f32_e32 v17, v10
	v_pk_mul_f32 v[14:15], v[58:59], v[14:15]
	v_lshlrev_b32_e32 v60, 16, v13
	v_cvt_pk_bf16_f32 v10, v14, v15
	v_lshlrev_b32_e32 v14, 16, v11
	v_and_b32_e32 v15, 0xffff0000, v11
	s_waitcnt lgkmcnt(0)
	v_sub_f32_e32 v11, v74, v62
	v_mul_f32_e32 v11, 0x3fb8aa3b, v11
	v_pk_mul_f32 v[14:15], v[16:17], v[14:15]
	v_exp_f32_e32 v16, v11
	v_sub_f32_e32 v11, v75, v63
	v_mul_f32_e32 v11, 0x3fb8aa3b, v11
	v_exp_f32_e32 v17, v11
	v_cvt_pk_bf16_f32 v11, v14, v15
	v_lshlrev_b32_e32 v14, 16, v12
	v_and_b32_e32 v15, 0xffff0000, v12
	v_pk_mul_f32 v[14:15], v[16:17], v[14:15]
	v_lshl_add_u32 v62, v90, 10, v84
	v_cvt_pk_bf16_f32 v12, v14, v15
	v_sub_f32_e32 v14, v72, v64
	v_mul_f32_e32 v14, 0x3fb8aa3b, v14
	v_exp_f32_e32 v58, v14
	v_sub_f32_e32 v14, v73, v65
	v_mul_f32_e32 v14, 0x3fb8aa3b, v14
	v_exp_f32_e32 v59, v14
	ds_read_b128 v[14:17], v62
	v_and_b32_e32 v61, 0xffff0000, v13
	v_mad_u32_u24 v63, v91, s0, v85
	v_pk_mul_f32 v[58:59], v[58:59], v[60:61]
	s_nop 0
	v_cvt_pk_bf16_f32 v13, v58, v59
	ds_read_b128 v[58:61], v62 offset:16
	s_waitcnt lgkmcnt(1)
	v_sub_f32_e32 v14, v54, v14
	v_sub_f32_e32 v15, v55, v15
	v_mul_f32_e32 v14, 0x3fb8aa3b, v14
	v_mul_f32_e32 v15, 0x3fb8aa3b, v15
	ds_write_b128 v63, v[10:13]
	v_lshlrev_b32_e32 v10, 16, v6
	v_and_b32_e32 v11, 0xffff0000, v6
	v_sub_f32_e32 v6, v56, v16
	v_exp_f32_e32 v14, v14
	v_exp_f32_e32 v15, v15
	v_mul_f32_e32 v6, 0x3fb8aa3b, v6
	v_exp_f32_e32 v12, v6
	v_sub_f32_e32 v6, v57, v17
	v_mul_f32_e32 v6, 0x3fb8aa3b, v6
	v_exp_f32_e32 v13, v6
	v_pk_mul_f32 v[10:11], v[14:15], v[10:11]
	v_lshlrev_b32_e32 v14, 16, v2
	v_cvt_pk_bf16_f32 v6, v10, v11
	v_lshlrev_b32_e32 v10, 16, v7
	v_and_b32_e32 v11, 0xffff0000, v7
	s_waitcnt lgkmcnt(1)
	v_sub_f32_e32 v7, v50, v58
	v_mul_f32_e32 v7, 0x3fb8aa3b, v7
	v_pk_mul_f32 v[10:11], v[12:13], v[10:11]
	v_exp_f32_e32 v12, v7
	v_sub_f32_e32 v7, v51, v59
	v_mul_f32_e32 v7, 0x3fb8aa3b, v7
	v_exp_f32_e32 v13, v7
	v_cvt_pk_bf16_f32 v7, v10, v11
	v_lshlrev_b32_e32 v10, 16, v8
	v_and_b32_e32 v11, 0xffff0000, v8
	v_sub_f32_e32 v8, v52, v60
	v_mul_f32_e32 v8, 0x3fb8aa3b, v8
	v_pk_mul_f32 v[10:11], v[12:13], v[10:11]
	v_exp_f32_e32 v12, v8
	v_sub_f32_e32 v8, v53, v61
	v_mul_f32_e32 v8, 0x3fb8aa3b, v8
	v_exp_f32_e32 v13, v8
	v_cvt_pk_bf16_f32 v8, v10, v11
	v_lshlrev_b32_e32 v10, 16, v9
	v_and_b32_e32 v11, 0xffff0000, v9
	v_pk_mul_f32 v[10:11], v[12:13], v[10:11]
	v_and_b32_e32 v15, 0xffff0000, v2
	v_cvt_pk_bf16_f32 v9, v10, v11
	v_mad_u32_u24 v10, v90, s0, v85
	ds_write_b128 v10, v[6:9]
	v_lshl_add_u32 v10, v89, 10, v84
	ds_read_b128 v[6:9], v10
	ds_read_b128 v[10:13], v10 offset:16
	s_waitcnt lgkmcnt(1)
	v_sub_f32_e32 v6, v54, v6
	v_sub_f32_e32 v7, v55, v7
	v_mul_f32_e32 v6, 0x3fb8aa3b, v6
	v_mul_f32_e32 v7, 0x3fb8aa3b, v7
	v_sub_f32_e32 v2, v56, v8
	v_exp_f32_e32 v6, v6
	v_exp_f32_e32 v7, v7
	v_mul_f32_e32 v2, 0x3fb8aa3b, v2
	v_exp_f32_e32 v8, v2
	v_sub_f32_e32 v2, v57, v9
	v_mul_f32_e32 v2, 0x3fb8aa3b, v2
	v_exp_f32_e32 v9, v2
	v_pk_mul_f32 v[6:7], v[6:7], v[14:15]
	s_nop 0
	v_cvt_pk_bf16_f32 v2, v6, v7
	v_lshlrev_b32_e32 v6, 16, v3
	v_and_b32_e32 v7, 0xffff0000, v3
	s_waitcnt lgkmcnt(0)
	v_sub_f32_e32 v3, v50, v10
	v_mul_f32_e32 v3, 0x3fb8aa3b, v3
	v_pk_mul_f32 v[6:7], v[8:9], v[6:7]
	v_exp_f32_e32 v8, v3
	v_sub_f32_e32 v3, v51, v11
	v_mul_f32_e32 v3, 0x3fb8aa3b, v3
	v_exp_f32_e32 v9, v3
	v_cvt_pk_bf16_f32 v3, v6, v7
	v_lshlrev_b32_e32 v6, 16, v4
	v_and_b32_e32 v7, 0xffff0000, v4
	v_sub_f32_e32 v4, v52, v12
	v_mul_f32_e32 v4, 0x3fb8aa3b, v4
	v_pk_mul_f32 v[6:7], v[8:9], v[6:7]
	v_exp_f32_e32 v8, v4
	v_sub_f32_e32 v4, v53, v13
	v_mul_f32_e32 v4, 0x3fb8aa3b, v4
	v_exp_f32_e32 v9, v4
	v_cvt_pk_bf16_f32 v4, v6, v7
	v_lshlrev_b32_e32 v6, 16, v5
	v_and_b32_e32 v7, 0xffff0000, v5
	v_pk_mul_f32 v[6:7], v[8:9], v[6:7]
	s_nop 0
	v_cvt_pk_bf16_f32 v5, v6, v7
	v_mad_u32_u24 v6, v89, s0, v85
	ds_write_b128 v6, v[2:5]
	s_and_saveexec_b64 s[0:1], vcc
	s_cbranch_execz .LBB0_389
	v_lshl_add_u32 v2, v0, 2, 0
	v_add_u32_e32 v3, 0x24000, v2
	ds_read_b32 v4, v2 offset:64512
	ds_read_b32 v5, v3
	v_lshl_or_b32 v2, s6, 8, v0
	v_ashrrev_i32_e32 v3, 31, v2
	v_lshl_add_u64 v[2:3], v[2:3], 2, s[58:59]
	v_add_co_u32_e32 v2, vcc, 0x180000, v2
	s_waitcnt lgkmcnt(0)
	v_add_f32_e32 v4, v4, v5
	v_mul_f32_e32 v4, 0x3fb8aa3b, v4
	v_exp_f32_e32 v4, v4
	v_addc_co_u32_e32 v3, vcc, 0, v3, vcc
	global_store_dword v[2:3], v4, off
